# G1 phase: half of the workgroups of every XCD (bid bit 3) start 8128 clocks later so their epilogue store bursts alternate
# baseline (speedup 1.0000x reference)
; __global__ void __launch_bounds__(512, 2) mega(Params P0) {
;     ...
;         else if (ph == 1) { pg8::Gemm g{(const bf16_t*)(dob + DO_ABF), (const bf16_t*)(dob + DO_W1T), NTOK, NPROJ, DM}; pg8::StaticOrder S; S.init(NTOK, NPROJ, G, bid);
;             EpiProj E{(bf16_t*)(ws + WS_PROJ), (const f32x2*)(dob + DO_ROPE), (bf16_t*)(dob + DO_HQ), P.in[6], P.in[7]}; pg8::gemm_phase(lds, g, S, E); }
.LBB0_588:
	s_andn2_b64 vcc, exec, s[2:3]
	s_cbranch_vccnz .LBB0_716
	s_bitcmp1_b32 s77, 3
	s_cbranch_scc0 .Lg1_nostag
	s_sleep 127
